# peer_q top-k: stage-1 insertion chains replaced by four 16-input odd-even merge sorts + three bitonic prune-merges, lane-pair merge replaced by a bitonic merge (same sorted lists, fewer VALU)
# speedup vs baseline: 1.0605x; 1.0040x over previous
; DI void phase_peer_q(const Params& p, int layer, u16* lds, const int WAVE_S) {
;     ...
; #pragma unroll
;       for (int i = 0; i < 16; ++i) t[i] = -3.0e38f;
; #pragma unroll
;       for (int nt = 0; nt < 4; ++nt)
; #pragma unroll
;         for (int i = 0; i < 16; ++i) {
;           const uint32_t n = nt * 32 + (i & 3) + 8 * (i >> 2) + 4 * h;
;           const float v = __uint_as_float((__float_as_uint(acc[nt][0][i]) & ~127u) | n);
;           ins16n(t, v, nt * 16 + i);
;         }
.Lpq_nopf:
	s_nop 7
	s_nop 7
	s_andn2_b64 vcc, exec, s[48:49]
	v_and_or_b32 v50, v50, s88, v123
	v_or_b32_e32 v0, 1, v123
	v_and_or_b32 v51, v51, s88, v0
	v_or_b32_e32 v0, 2, v123
	v_and_or_b32 v52, v52, s88, v0
	v_or_b32_e32 v0, 3, v123
	v_and_or_b32 v53, v53, s88, v0
	v_or_b32_e32 v0, 8, v123
	v_and_or_b32 v54, v54, s88, v0
	v_or_b32_e32 v0, 9, v123
	v_and_or_b32 v55, v55, s88, v0
	v_or_b32_e32 v0, 10, v123
	v_and_or_b32 v56, v56, s88, v0
	v_or_b32_e32 v0, 11, v123
	v_and_or_b32 v57, v57, s88, v0
	v_or_b32_e32 v0, 16, v123
	v_and_or_b32 v58, v58, s88, v0
	v_or_b32_e32 v0, 17, v123
	v_and_or_b32 v59, v59, s88, v0
	v_or_b32_e32 v0, 18, v123
	v_and_or_b32 v60, v60, s88, v0
	v_or_b32_e32 v0, 19, v123
	v_and_or_b32 v61, v61, s88, v0
	v_or_b32_e32 v0, 24, v123
	v_and_or_b32 v62, v62, s88, v0
	v_or_b32_e32 v0, 25, v123
	v_and_or_b32 v63, v63, s88, v0
	v_or_b32_e32 v0, 26, v123
	v_and_or_b32 v64, v64, s88, v0
	v_or_b32_e32 v0, 27, v123
	v_and_or_b32 v65, v65, s88, v0
	v_or_b32_e32 v0, 32, v123
	v_and_or_b32 v34, v34, s88, v0
	v_or_b32_e32 v0, 33, v123
	v_and_or_b32 v35, v35, s88, v0
	v_or_b32_e32 v0, 34, v123
	v_and_or_b32 v36, v36, s88, v0
	v_or_b32_e32 v0, 35, v123
	v_and_or_b32 v37, v37, s88, v0
	v_or_b32_e32 v0, 40, v123
	v_and_or_b32 v38, v38, s88, v0
	v_or_b32_e32 v0, 41, v123
	v_and_or_b32 v39, v39, s88, v0
	v_or_b32_e32 v0, 42, v123
	v_and_or_b32 v40, v40, s88, v0
	v_or_b32_e32 v0, 43, v123
	v_and_or_b32 v41, v41, s88, v0
	v_or_b32_e32 v0, 48, v123
	v_and_or_b32 v42, v42, s88, v0
	v_or_b32_e32 v0, 49, v123
	v_and_or_b32 v43, v43, s88, v0
	v_or_b32_e32 v0, 50, v123
	v_and_or_b32 v44, v44, s88, v0
	v_or_b32_e32 v0, 51, v123
	v_and_or_b32 v45, v45, s88, v0
	v_or_b32_e32 v0, 56, v123
	v_and_or_b32 v46, v46, s88, v0
	v_or_b32_e32 v0, 57, v123
	v_and_or_b32 v47, v47, s88, v0
	v_or_b32_e32 v0, 58, v123
	v_and_or_b32 v48, v48, s88, v0
	v_or_b32_e32 v0, 59, v123
	v_and_or_b32 v49, v49, s88, v0
	v_or_b32_e32 v0, 64, v123
	v_and_or_b32 v18, v18, s88, v0
	v_or_b32_e32 v0, 65, v123
	v_and_or_b32 v19, v19, s88, v0
	v_or_b32_e32 v0, 66, v123
	v_and_or_b32 v20, v20, s88, v0
	v_or_b32_e32 v0, 67, v123
	v_and_or_b32 v21, v21, s88, v0
	v_or_b32_e32 v0, 72, v123
	v_and_or_b32 v22, v22, s88, v0
	v_or_b32_e32 v0, 73, v123
	v_and_or_b32 v23, v23, s88, v0
	v_or_b32_e32 v0, 74, v123
	v_and_or_b32 v24, v24, s88, v0
	v_or_b32_e32 v0, 75, v123
	v_and_or_b32 v25, v25, s88, v0
	v_or_b32_e32 v0, 80, v123
	v_and_or_b32 v26, v26, s88, v0
	v_or_b32_e32 v0, 81, v123
	v_and_or_b32 v27, v27, s88, v0
	v_or_b32_e32 v0, 82, v123
	v_and_or_b32 v28, v28, s88, v0
	v_or_b32_e32 v0, 83, v123
	v_and_or_b32 v29, v29, s88, v0
	v_or_b32_e32 v0, 88, v123
	v_and_or_b32 v30, v30, s88, v0
	v_or_b32_e32 v0, 89, v123
	v_and_or_b32 v31, v31, s88, v0
	v_or_b32_e32 v0, 90, v123
	v_and_or_b32 v32, v32, s88, v0
	v_or_b32_e32 v0, 91, v123
	v_and_or_b32 v33, v33, s88, v0
	v_or_b32_e32 v0, 96, v123
	v_and_or_b32 v2, v2, s88, v0
	v_or_b32_e32 v0, 97, v123
	v_and_or_b32 v3, v3, s88, v0
	v_or_b32_e32 v0, 98, v123
	v_and_or_b32 v4, v4, s88, v0
	v_or_b32_e32 v0, 99, v123
	v_and_or_b32 v5, v5, s88, v0
	v_or_b32_e32 v0, 104, v123
	v_and_or_b32 v6, v6, s88, v0
	v_or_b32_e32 v0, 105, v123
	v_and_or_b32 v7, v7, s88, v0
	v_or_b32_e32 v0, 106, v123
	v_and_or_b32 v8, v8, s88, v0
	v_or_b32_e32 v0, 107, v123
	v_and_or_b32 v9, v9, s88, v0
	v_and_or_b32 v10, v10, s88, v125
	v_and_or_b32 v11, v11, s88, v126
	v_and_or_b32 v12, v12, s88, v127
	v_and_or_b32 v13, v13, s88, v128
	v_and_or_b32 v14, v14, s88, v129
	v_and_or_b32 v15, v15, s88, v130
	v_and_or_b32 v16, v16, s88, v131
	v_and_or_b32 v17, v17, s88, v132
	v_min_f32_e32 v134, v2, v3
	v_max_f32_e32 v2, v2, v3
	v_min_f32_e32 v135, v4, v5
	v_max_f32_e32 v4, v4, v5
	v_min_f32_e32 v136, v2, v4
	v_max_f32_e32 v2, v2, v4
	v_min_f32_e32 v137, v134, v135
	v_max_f32_e32 v134, v134, v135
	v_min_f32_e32 v138, v134, v136
	v_max_f32_e32 v134, v134, v136
	v_min_f32_e32 v139, v6, v7
	v_max_f32_e32 v6, v6, v7
	v_min_f32_e32 v140, v8, v9
	v_max_f32_e32 v8, v8, v9
	v_min_f32_e32 v141, v6, v8
	v_max_f32_e32 v6, v6, v8
	v_min_f32_e32 v142, v139, v140
	v_max_f32_e32 v139, v139, v140
	v_min_f32_e32 v143, v139, v141
	v_max_f32_e32 v139, v139, v141
	v_min_f32_e32 v144, v2, v6
	v_max_f32_e32 v2, v2, v6
	v_min_f32_e32 v145, v138, v143
	v_max_f32_e32 v138, v138, v143
	v_min_f32_e32 v148, v138, v144
	v_max_f32_e32 v138, v138, v144
	v_min_f32_e32 v149, v134, v139
	v_max_f32_e32 v134, v134, v139
	v_min_f32_e32 v150, v137, v142
	v_max_f32_e32 v137, v137, v142
	v_min_f32_e32 v151, v137, v149
	v_max_f32_e32 v137, v137, v149
	v_min_f32_e32 v152, v134, v138
	v_max_f32_e32 v134, v134, v138
	v_min_f32_e32 v153, v137, v148
	v_max_f32_e32 v137, v137, v148
	v_min_f32_e32 v154, v151, v145
	v_max_f32_e32 v151, v151, v145
	v_min_f32_e32 v155, v10, v11
	v_max_f32_e32 v10, v10, v11
	v_min_f32_e32 v0, v12, v13
	v_max_f32_e32 v12, v12, v13
	v_min_f32_e32 v3, v10, v12
	v_max_f32_e32 v10, v10, v12
	v_min_f32_e32 v5, v155, v0
	v_max_f32_e32 v155, v155, v0
	v_min_f32_e32 v4, v155, v3
	v_max_f32_e32 v155, v155, v3
	v_min_f32_e32 v135, v14, v15
	v_max_f32_e32 v14, v14, v15
	v_min_f32_e32 v136, v16, v17
	v_max_f32_e32 v16, v16, v17
	v_min_f32_e32 v7, v14, v16
	v_max_f32_e32 v14, v14, v16
	v_min_f32_e32 v9, v135, v136
	v_max_f32_e32 v135, v135, v136
	v_min_f32_e32 v8, v135, v7
	v_max_f32_e32 v135, v135, v7
	v_min_f32_e32 v140, v10, v14
	v_max_f32_e32 v10, v10, v14
	v_min_f32_e32 v141, v4, v8
	v_max_f32_e32 v4, v4, v8
	v_min_f32_e32 v6, v4, v140
	v_max_f32_e32 v4, v4, v140
	v_min_f32_e32 v143, v155, v135
	v_max_f32_e32 v155, v155, v135
	v_min_f32_e32 v144, v5, v9
	v_max_f32_e32 v5, v5, v9
	v_min_f32_e32 v139, v5, v143
; DI void phase_peer_q(const Params& p, int layer, u16* lds, const int WAVE_S) {
;     ...
; #pragma unroll
;       for (int i = 0; i < 16; ++i) t[i] = -3.0e38f;
; #pragma unroll
;       for (int nt = 0; nt < 4; ++nt)
; #pragma unroll
;         for (int i = 0; i < 16; ++i) {
;           const uint32_t n = nt * 32 + (i & 3) + 8 * (i >> 2) + 4 * h;
;           const float v = __uint_as_float((__float_as_uint(acc[nt][0][i]) & ~127u) | n);
;           ins16n(t, v, nt * 16 + i);
;         }
	v_max_f32_e32 v5, v5, v143
	v_min_f32_e32 v142, v155, v4
	v_max_f32_e32 v155, v155, v4
	v_min_f32_e32 v149, v5, v6
	v_max_f32_e32 v5, v5, v6
	v_min_f32_e32 v138, v139, v141
	v_max_f32_e32 v139, v139, v141
	v_min_f32_e32 v148, v2, v10
	v_max_f32_e32 v2, v2, v10
	v_min_f32_e32 v145, v153, v149
	v_max_f32_e32 v153, v153, v149
	v_min_f32_e32 v11, v153, v148
	v_max_f32_e32 v153, v153, v148
	v_min_f32_e32 v13, v152, v142
	v_max_f32_e32 v152, v152, v142
	v_min_f32_e32 v12, v154, v138
	v_max_f32_e32 v154, v154, v138
	v_min_f32_e32 v0, v154, v13
	v_max_f32_e32 v154, v154, v13
	v_min_f32_e32 v3, v152, v153
	v_max_f32_e32 v152, v152, v153
	v_min_f32_e32 v15, v154, v11
	v_max_f32_e32 v154, v154, v11
	v_min_f32_e32 v17, v0, v145
	v_max_f32_e32 v0, v0, v145
	v_min_f32_e32 v16, v134, v155
	v_max_f32_e32 v134, v134, v155
	v_min_f32_e32 v136, v151, v139
	v_max_f32_e32 v151, v151, v139
	v_min_f32_e32 v7, v151, v16
	v_max_f32_e32 v151, v151, v16
	v_min_f32_e32 v14, v137, v5
	v_max_f32_e32 v137, v137, v5
	v_min_f32_e32 v8, v150, v144
	v_max_f32_e32 v150, v150, v144
	v_min_f32_e32 v140, v150, v14
	v_max_f32_e32 v150, v150, v14
	v_min_f32_e32 v135, v137, v151
	v_max_f32_e32 v137, v137, v151
	v_min_f32_e32 v9, v150, v7
	v_max_f32_e32 v150, v150, v7
	v_min_f32_e32 v143, v140, v136
	v_max_f32_e32 v140, v140, v136
	v_min_f32_e32 v4, v134, v152
	v_max_f32_e32 v134, v134, v152
	v_min_f32_e32 v6, v137, v3
	v_max_f32_e32 v137, v137, v3
	v_min_f32_e32 v141, v135, v154
	v_max_f32_e32 v135, v135, v154
	v_min_f32_e32 v10, v150, v15
	v_max_f32_e32 v150, v150, v15
	v_min_f32_e32 v149, v9, v0
	v_max_f32_e32 v9, v9, v0
	v_min_f32_e32 v148, v140, v17
	v_max_f32_e32 v140, v140, v17
	v_min_f32_e32 v142, v143, v12
	v_max_f32_e32 v143, v143, v12
	v_min_f32_e32 v138, v18, v19
	v_max_f32_e32 v18, v18, v19
	v_min_f32_e32 v13, v20, v21
	v_max_f32_e32 v20, v20, v21
	v_min_f32_e32 v153, v18, v20
	v_max_f32_e32 v18, v18, v20
	v_min_f32_e32 v11, v138, v13
	v_max_f32_e32 v138, v138, v13
	v_min_f32_e32 v145, v138, v153
	v_max_f32_e32 v138, v138, v153
	v_min_f32_e32 v155, v22, v23
	v_max_f32_e32 v22, v22, v23
	v_min_f32_e32 v139, v24, v25
	v_max_f32_e32 v24, v24, v25
	v_min_f32_e32 v16, v22, v24
	v_max_f32_e32 v22, v22, v24
	v_min_f32_e32 v5, v155, v139
	v_max_f32_e32 v155, v155, v139
	v_min_f32_e32 v144, v155, v16
	v_max_f32_e32 v155, v155, v16
	v_min_f32_e32 v14, v18, v22
	v_max_f32_e32 v18, v18, v22
	v_min_f32_e32 v151, v145, v144
	v_max_f32_e32 v145, v145, v144
	v_min_f32_e32 v7, v145, v14
	v_max_f32_e32 v145, v145, v14
	v_min_f32_e32 v136, v138, v155
	v_max_f32_e32 v138, v138, v155
	v_min_f32_e32 v152, v11, v5
	v_max_f32_e32 v11, v11, v5
	v_min_f32_e32 v3, v11, v136
	v_max_f32_e32 v11, v11, v136
	v_min_f32_e32 v154, v138, v145
	v_max_f32_e32 v138, v138, v145
	v_min_f32_e32 v15, v11, v7
	v_max_f32_e32 v11, v11, v7
	v_min_f32_e32 v0, v3, v151
	v_max_f32_e32 v3, v3, v151
	v_min_f32_e32 v17, v26, v27
	v_max_f32_e32 v26, v26, v27
	v_min_f32_e32 v12, v28, v29
	v_max_f32_e32 v28, v28, v29
	v_min_f32_e32 v19, v26, v28
	v_max_f32_e32 v26, v26, v28
	v_min_f32_e32 v21, v17, v12
	v_max_f32_e32 v17, v17, v12
	v_min_f32_e32 v20, v17, v19
	v_max_f32_e32 v17, v17, v19
	v_min_f32_e32 v13, v30, v31
	v_max_f32_e32 v30, v30, v31
	v_min_f32_e32 v153, v32, v33
	v_max_f32_e32 v32, v32, v33
	v_min_f32_e32 v23, v30, v32
	v_max_f32_e32 v30, v30, v32
	v_min_f32_e32 v25, v13, v153
	v_max_f32_e32 v13, v13, v153
	v_min_f32_e32 v24, v13, v23
	v_max_f32_e32 v13, v13, v23
	v_min_f32_e32 v139, v26, v30
	v_max_f32_e32 v26, v26, v30
	v_min_f32_e32 v16, v20, v24
	v_max_f32_e32 v20, v20, v24
	v_min_f32_e32 v22, v20, v139
	v_max_f32_e32 v20, v20, v139
	v_min_f32_e32 v144, v17, v13
	v_max_f32_e32 v17, v17, v13
	v_min_f32_e32 v14, v21, v25
	v_max_f32_e32 v21, v21, v25
	v_min_f32_e32 v155, v21, v144
	v_max_f32_e32 v21, v21, v144
	v_min_f32_e32 v5, v17, v20
	v_max_f32_e32 v17, v17, v20
	v_min_f32_e32 v136, v21, v22
	v_max_f32_e32 v21, v21, v22
	v_min_f32_e32 v145, v155, v16
	v_max_f32_e32 v155, v155, v16
	v_min_f32_e32 v7, v18, v26
	v_max_f32_e32 v18, v18, v26
	v_min_f32_e32 v151, v15, v136
	v_max_f32_e32 v15, v15, v136
	v_min_f32_e32 v27, v15, v7
	v_max_f32_e32 v15, v15, v7
	v_min_f32_e32 v29, v154, v5
	v_max_f32_e32 v154, v154, v5
	v_min_f32_e32 v28, v0, v145
	v_max_f32_e32 v0, v0, v145
	v_min_f32_e32 v12, v0, v29
	v_max_f32_e32 v0, v0, v29
	v_min_f32_e32 v19, v154, v15
	v_max_f32_e32 v154, v154, v15
	v_min_f32_e32 v31, v0, v27
	v_max_f32_e32 v0, v0, v27
	v_min_f32_e32 v33, v12, v151
	v_max_f32_e32 v12, v12, v151
	v_min_f32_e32 v32, v138, v17
	v_max_f32_e32 v138, v138, v17
	v_min_f32_e32 v153, v3, v155
	v_max_f32_e32 v3, v3, v155
	v_min_f32_e32 v23, v3, v32
	v_max_f32_e32 v3, v3, v32
	v_min_f32_e32 v30, v11, v21
	v_max_f32_e32 v11, v11, v21
	v_min_f32_e32 v24, v152, v14
	v_max_f32_e32 v152, v152, v14
	v_min_f32_e32 v139, v152, v30
	v_max_f32_e32 v152, v152, v30
	v_min_f32_e32 v13, v11, v3
	v_max_f32_e32 v11, v11, v3
	v_min_f32_e32 v25, v152, v23
	v_max_f32_e32 v152, v152, v23
	v_min_f32_e32 v144, v139, v153
	v_max_f32_e32 v139, v139, v153
	v_min_f32_e32 v20, v138, v154
	v_max_f32_e32 v138, v138, v154
	v_min_f32_e32 v22, v11, v19
	v_max_f32_e32 v11, v11, v19
	v_min_f32_e32 v16, v13, v0
	v_max_f32_e32 v13, v13, v0
	v_min_f32_e32 v26, v152, v31
	v_max_f32_e32 v152, v152, v31
	v_min_f32_e32 v136, v25, v12
	v_max_f32_e32 v25, v25, v12
	v_min_f32_e32 v7, v139, v33
	v_max_f32_e32 v139, v139, v33
	v_min_f32_e32 v5, v144, v28
	v_max_f32_e32 v144, v144, v28
	v_min_f32_e32 v145, v34, v35
	v_max_f32_e32 v34, v34, v35
	v_min_f32_e32 v29, v36, v37
	v_max_f32_e32 v36, v36, v37
	v_min_f32_e32 v15, v34, v36
	v_max_f32_e32 v34, v34, v36
; DI void phase_peer_q(const Params& p, int layer, u16* lds, const int WAVE_S) {
;     ...
; #pragma unroll
;       for (int i = 0; i < 16; ++i) t[i] = -3.0e38f;
; #pragma unroll
;       for (int nt = 0; nt < 4; ++nt)
; #pragma unroll
;         for (int i = 0; i < 16; ++i) {
;           const uint32_t n = nt * 32 + (i & 3) + 8 * (i >> 2) + 4 * h;
;           const float v = __uint_as_float((__float_as_uint(acc[nt][0][i]) & ~127u) | n);
;           ins16n(t, v, nt * 16 + i);
;         }
	v_min_f32_e32 v27, v145, v29
	v_max_f32_e32 v145, v145, v29
	v_min_f32_e32 v151, v145, v15
	v_max_f32_e32 v145, v145, v15
	v_min_f32_e32 v17, v38, v39
	v_max_f32_e32 v38, v38, v39
	v_min_f32_e32 v155, v40, v41
	v_max_f32_e32 v40, v40, v41
	v_min_f32_e32 v32, v38, v40
	v_max_f32_e32 v38, v38, v40
	v_min_f32_e32 v21, v17, v155
	v_max_f32_e32 v17, v17, v155
	v_min_f32_e32 v14, v17, v32
	v_max_f32_e32 v17, v17, v32
	v_min_f32_e32 v30, v34, v38
	v_max_f32_e32 v34, v34, v38
	v_min_f32_e32 v3, v151, v14
	v_max_f32_e32 v151, v151, v14
	v_min_f32_e32 v23, v151, v30
	v_max_f32_e32 v151, v151, v30
	v_min_f32_e32 v153, v145, v17
	v_max_f32_e32 v145, v145, v17
	v_min_f32_e32 v154, v27, v21
	v_max_f32_e32 v27, v27, v21
	v_min_f32_e32 v19, v27, v153
	v_max_f32_e32 v27, v27, v153
	v_min_f32_e32 v0, v145, v151
	v_max_f32_e32 v145, v145, v151
	v_min_f32_e32 v31, v27, v23
	v_max_f32_e32 v27, v27, v23
	v_min_f32_e32 v12, v19, v3
	v_max_f32_e32 v19, v19, v3
	v_min_f32_e32 v33, v42, v43
	v_max_f32_e32 v42, v42, v43
	v_min_f32_e32 v28, v44, v45
	v_max_f32_e32 v44, v44, v45
	v_min_f32_e32 v35, v42, v44
	v_max_f32_e32 v42, v42, v44
	v_min_f32_e32 v37, v33, v28
	v_max_f32_e32 v33, v33, v28
	v_min_f32_e32 v36, v33, v35
	v_max_f32_e32 v33, v33, v35
	v_min_f32_e32 v29, v46, v47
	v_max_f32_e32 v46, v46, v47
	v_min_f32_e32 v15, v48, v49
	v_max_f32_e32 v48, v48, v49
	v_min_f32_e32 v39, v46, v48
	v_max_f32_e32 v46, v46, v48
	v_min_f32_e32 v41, v29, v15
	v_max_f32_e32 v29, v29, v15
	v_min_f32_e32 v40, v29, v39
	v_max_f32_e32 v29, v29, v39
	v_min_f32_e32 v155, v42, v46
	v_max_f32_e32 v42, v42, v46
	v_min_f32_e32 v32, v36, v40
	v_max_f32_e32 v36, v36, v40
	v_min_f32_e32 v38, v36, v155
	v_max_f32_e32 v36, v36, v155
	v_min_f32_e32 v14, v33, v29
	v_max_f32_e32 v33, v33, v29
	v_min_f32_e32 v30, v37, v41
	v_max_f32_e32 v37, v37, v41
	v_min_f32_e32 v17, v37, v14
	v_max_f32_e32 v37, v37, v14
	v_min_f32_e32 v21, v33, v36
	v_max_f32_e32 v33, v33, v36
	v_min_f32_e32 v153, v37, v38
	v_max_f32_e32 v37, v37, v38
	v_min_f32_e32 v151, v17, v32
	v_max_f32_e32 v17, v17, v32
	v_min_f32_e32 v23, v34, v42
	v_max_f32_e32 v34, v34, v42
	v_min_f32_e32 v3, v31, v153
	v_max_f32_e32 v31, v31, v153
	v_min_f32_e32 v43, v31, v23
	v_max_f32_e32 v31, v31, v23
	v_min_f32_e32 v45, v0, v21
	v_max_f32_e32 v0, v0, v21
	v_min_f32_e32 v44, v12, v151
	v_max_f32_e32 v12, v12, v151
	v_min_f32_e32 v28, v12, v45
	v_max_f32_e32 v12, v12, v45
	v_min_f32_e32 v35, v0, v31
	v_max_f32_e32 v0, v0, v31
	v_min_f32_e32 v47, v12, v43
	v_max_f32_e32 v12, v12, v43
	v_min_f32_e32 v49, v28, v3
	v_max_f32_e32 v28, v28, v3
	v_min_f32_e32 v48, v145, v33
	v_max_f32_e32 v145, v145, v33
	v_min_f32_e32 v15, v19, v17
	v_max_f32_e32 v19, v19, v17
	v_min_f32_e32 v39, v19, v48
	v_max_f32_e32 v19, v19, v48
	v_min_f32_e32 v46, v27, v37
	v_max_f32_e32 v27, v27, v37
	v_min_f32_e32 v40, v154, v30
	v_max_f32_e32 v154, v154, v30
	v_min_f32_e32 v155, v154, v46
	v_max_f32_e32 v154, v154, v46
	v_min_f32_e32 v29, v27, v19
	v_max_f32_e32 v27, v27, v19
	v_min_f32_e32 v41, v154, v39
	v_max_f32_e32 v154, v154, v39
	v_min_f32_e32 v14, v155, v15
	v_max_f32_e32 v155, v155, v15
	v_min_f32_e32 v36, v145, v0
	v_max_f32_e32 v145, v145, v0
	v_min_f32_e32 v38, v27, v35
	v_max_f32_e32 v27, v27, v35
	v_min_f32_e32 v32, v29, v12
	v_max_f32_e32 v29, v29, v12
	v_min_f32_e32 v42, v154, v47
	v_max_f32_e32 v154, v154, v47
	v_min_f32_e32 v153, v41, v28
	v_max_f32_e32 v41, v41, v28
	v_min_f32_e32 v23, v155, v49
	v_max_f32_e32 v155, v155, v49
	v_min_f32_e32 v21, v14, v44
	v_max_f32_e32 v14, v14, v44
	v_min_f32_e32 v151, v50, v51
	v_max_f32_e32 v50, v50, v51
	v_min_f32_e32 v45, v52, v53
	v_max_f32_e32 v52, v52, v53
	v_min_f32_e32 v31, v50, v52
	v_max_f32_e32 v50, v50, v52
	v_min_f32_e32 v43, v151, v45
	v_max_f32_e32 v151, v151, v45
	v_min_f32_e32 v3, v151, v31
	v_max_f32_e32 v151, v151, v31
	v_min_f32_e32 v33, v54, v55
	v_max_f32_e32 v54, v54, v55
	v_min_f32_e32 v17, v56, v57
	v_max_f32_e32 v56, v56, v57
	v_min_f32_e32 v48, v54, v56
	v_max_f32_e32 v54, v54, v56
	v_min_f32_e32 v37, v33, v17
	v_max_f32_e32 v33, v33, v17
	v_min_f32_e32 v30, v33, v48
	v_max_f32_e32 v33, v33, v48
	v_min_f32_e32 v46, v50, v54
	v_max_f32_e32 v50, v50, v54
	v_min_f32_e32 v19, v3, v30
	v_max_f32_e32 v3, v3, v30
	v_min_f32_e32 v39, v3, v46
	v_max_f32_e32 v3, v3, v46
	v_min_f32_e32 v15, v151, v33
	v_max_f32_e32 v151, v151, v33
	v_min_f32_e32 v0, v43, v37
	v_max_f32_e32 v43, v43, v37
	v_min_f32_e32 v35, v43, v15
	v_max_f32_e32 v43, v43, v15
	v_min_f32_e32 v12, v151, v3
	v_max_f32_e32 v151, v151, v3
	v_min_f32_e32 v47, v43, v39
	v_max_f32_e32 v43, v43, v39
	v_min_f32_e32 v28, v35, v19
	v_max_f32_e32 v35, v35, v19
	v_min_f32_e32 v49, v58, v59
	v_max_f32_e32 v58, v58, v59
	v_min_f32_e32 v44, v60, v61
	v_max_f32_e32 v60, v60, v61
	v_min_f32_e32 v51, v58, v60
	v_max_f32_e32 v58, v58, v60
	v_min_f32_e32 v53, v49, v44
	v_max_f32_e32 v49, v49, v44
	v_min_f32_e32 v52, v49, v51
	v_max_f32_e32 v49, v49, v51
	v_min_f32_e32 v45, v62, v63
	v_max_f32_e32 v62, v62, v63
	v_min_f32_e32 v31, v64, v65
	v_max_f32_e32 v64, v64, v65
	v_min_f32_e32 v55, v62, v64
	v_max_f32_e32 v62, v62, v64
	v_min_f32_e32 v57, v45, v31
	v_max_f32_e32 v45, v45, v31
	v_min_f32_e32 v56, v45, v55
	v_max_f32_e32 v45, v45, v55
	v_min_f32_e32 v17, v58, v62
	v_max_f32_e32 v58, v58, v62
	v_min_f32_e32 v48, v52, v56
	v_max_f32_e32 v52, v52, v56
	v_min_f32_e32 v54, v52, v17
	v_max_f32_e32 v52, v52, v17
	v_min_f32_e32 v30, v49, v45
	v_max_f32_e32 v49, v49, v45
	v_min_f32_e32 v46, v53, v57
	v_max_f32_e32 v53, v53, v57
	v_min_f32_e32 v33, v53, v30
	v_max_f32_e32 v53, v53, v30
	v_min_f32_e32 v37, v49, v52
	v_max_f32_e32 v49, v49, v52
	v_min_f32_e32 v15, v53, v54
; DI void phase_peer_q(const Params& p, int layer, u16* lds, const int WAVE_S) {
;     ...
; #pragma unroll
;       for (int i = 0; i < 16; ++i) t[i] = -3.0e38f;
; #pragma unroll
;       for (int nt = 0; nt < 4; ++nt)
; #pragma unroll
;         for (int i = 0; i < 16; ++i) {
;           const uint32_t n = nt * 32 + (i & 3) + 8 * (i >> 2) + 4 * h;
;           const float v = __uint_as_float((__float_as_uint(acc[nt][0][i]) & ~127u) | n);
;           ins16n(t, v, nt * 16 + i);
;         }
	v_max_f32_e32 v53, v53, v54
	v_min_f32_e32 v3, v33, v48
	v_max_f32_e32 v33, v33, v48
	v_min_f32_e32 v39, v50, v58
	v_max_f32_e32 v50, v50, v58
	v_min_f32_e32 v19, v47, v15
	v_max_f32_e32 v47, v47, v15
	v_min_f32_e32 v59, v47, v39
	v_max_f32_e32 v47, v47, v39
	v_min_f32_e32 v61, v12, v37
	v_max_f32_e32 v12, v12, v37
	v_min_f32_e32 v60, v28, v3
	v_max_f32_e32 v28, v28, v3
	v_min_f32_e32 v44, v28, v61
	v_max_f32_e32 v28, v28, v61
	v_min_f32_e32 v51, v12, v47
	v_max_f32_e32 v12, v12, v47
	v_min_f32_e32 v63, v28, v59
	v_max_f32_e32 v28, v28, v59
	v_min_f32_e32 v65, v44, v19
	v_max_f32_e32 v44, v44, v19
	v_min_f32_e32 v64, v151, v49
	v_max_f32_e32 v151, v151, v49
	v_min_f32_e32 v31, v35, v33
	v_max_f32_e32 v35, v35, v33
	v_min_f32_e32 v55, v35, v64
	v_max_f32_e32 v35, v35, v64
	v_min_f32_e32 v62, v43, v53
	v_max_f32_e32 v43, v43, v53
	v_min_f32_e32 v56, v0, v46
	v_max_f32_e32 v0, v0, v46
	v_min_f32_e32 v17, v0, v62
	v_max_f32_e32 v0, v0, v62
	v_min_f32_e32 v45, v43, v35
	v_max_f32_e32 v43, v43, v35
	v_min_f32_e32 v57, v0, v55
	v_max_f32_e32 v0, v0, v55
	v_min_f32_e32 v30, v17, v31
	v_max_f32_e32 v17, v17, v31
	v_min_f32_e32 v52, v151, v12
	v_max_f32_e32 v151, v151, v12
	v_min_f32_e32 v54, v43, v51
	v_max_f32_e32 v43, v43, v51
	v_min_f32_e32 v48, v45, v28
	v_max_f32_e32 v45, v45, v28
	v_min_f32_e32 v58, v0, v63
	v_max_f32_e32 v0, v0, v63
	v_min_f32_e32 v15, v57, v44
	v_max_f32_e32 v57, v57, v44
	v_min_f32_e32 v39, v17, v65
	v_max_f32_e32 v17, v17, v65
	v_min_f32_e32 v37, v30, v60
	v_max_f32_e32 v30, v30, v60
	v_max_f32_e32 v2, v2, v24
	v_max_f32_e32 v134, v134, v5
	v_max_f32_e32 v4, v4, v144
	v_max_f32_e32 v137, v137, v7
	v_max_f32_e32 v6, v6, v139
	v_max_f32_e32 v135, v135, v136
	v_max_f32_e32 v141, v141, v25
	v_max_f32_e32 v150, v150, v26
	v_max_f32_e32 v10, v10, v152
	v_max_f32_e32 v9, v9, v16
	v_max_f32_e32 v149, v149, v13
	v_max_f32_e32 v140, v140, v22
	v_max_f32_e32 v148, v148, v11
	v_max_f32_e32 v143, v143, v20
	v_max_f32_e32 v142, v142, v138
	v_max_f32_e32 v8, v8, v18
	v_min_f32_e32 v3, v2, v10
	v_max_f32_e32 v2, v2, v10
	v_min_f32_e32 v61, v134, v9
	v_max_f32_e32 v134, v134, v9
	v_min_f32_e32 v47, v4, v149
	v_max_f32_e32 v4, v4, v149
	v_min_f32_e32 v59, v137, v140
	v_max_f32_e32 v137, v137, v140
	v_min_f32_e32 v19, v6, v148
	v_max_f32_e32 v6, v6, v148
	v_min_f32_e32 v49, v135, v143
	v_max_f32_e32 v135, v135, v143
	v_min_f32_e32 v33, v141, v142
	v_max_f32_e32 v141, v141, v142
	v_min_f32_e32 v64, v150, v8
	v_max_f32_e32 v150, v150, v8
	v_min_f32_e32 v53, v2, v6
	v_max_f32_e32 v2, v2, v6
	v_min_f32_e32 v46, v134, v135
	v_max_f32_e32 v134, v134, v135
	v_min_f32_e32 v62, v4, v141
	v_max_f32_e32 v4, v4, v141
	v_min_f32_e32 v35, v137, v150
	v_max_f32_e32 v137, v137, v150
	v_min_f32_e32 v55, v3, v19
	v_max_f32_e32 v3, v3, v19
	v_min_f32_e32 v31, v61, v49
	v_max_f32_e32 v61, v61, v49
	v_min_f32_e32 v12, v47, v33
	v_max_f32_e32 v47, v47, v33
	v_min_f32_e32 v51, v59, v64
	v_max_f32_e32 v59, v59, v64
	v_min_f32_e32 v28, v2, v4
	v_max_f32_e32 v2, v2, v4
	v_min_f32_e32 v63, v134, v137
	v_max_f32_e32 v134, v134, v137
	v_min_f32_e32 v44, v53, v62
	v_max_f32_e32 v53, v53, v62
	v_min_f32_e32 v65, v46, v35
	v_max_f32_e32 v46, v46, v35
	v_min_f32_e32 v60, v3, v47
	v_max_f32_e32 v3, v3, v47
	v_min_f32_e32 v18, v61, v59
	v_max_f32_e32 v61, v61, v59
	v_min_f32_e32 v138, v55, v12
	v_max_f32_e32 v55, v55, v12
	v_min_f32_e32 v20, v31, v51
	v_max_f32_e32 v31, v31, v51
	v_min_f32_e32 v11, v2, v134
	v_max_f32_e32 v2, v2, v134
	v_min_f32_e32 v22, v28, v63
	v_max_f32_e32 v28, v28, v63
	v_min_f32_e32 v13, v53, v46
	v_max_f32_e32 v53, v53, v46
	v_min_f32_e32 v16, v44, v65
	v_max_f32_e32 v44, v44, v65
	v_min_f32_e32 v152, v3, v61
	v_max_f32_e32 v3, v3, v61
	v_min_f32_e32 v26, v60, v18
	v_max_f32_e32 v60, v60, v18
	v_min_f32_e32 v25, v55, v31
	v_max_f32_e32 v55, v55, v31
	v_min_f32_e32 v136, v138, v20
	v_max_f32_e32 v138, v138, v20
	v_max_f32_e32 v34, v34, v56
	v_max_f32_e32 v145, v145, v37
	v_max_f32_e32 v36, v36, v30
	v_max_f32_e32 v27, v27, v39
	v_max_f32_e32 v38, v38, v17
	v_max_f32_e32 v29, v29, v15
	v_max_f32_e32 v32, v32, v57
	v_max_f32_e32 v154, v154, v58
	v_max_f32_e32 v42, v42, v0
	v_max_f32_e32 v41, v41, v48
	v_max_f32_e32 v153, v153, v45
	v_max_f32_e32 v155, v155, v54
	v_max_f32_e32 v23, v23, v43
	v_max_f32_e32 v14, v14, v52
	v_max_f32_e32 v21, v21, v151
	v_max_f32_e32 v40, v40, v50
	v_min_f32_e32 v139, v34, v42
	v_max_f32_e32 v34, v34, v42
	v_min_f32_e32 v7, v145, v41
	v_max_f32_e32 v145, v145, v41
	v_min_f32_e32 v144, v36, v153
	v_max_f32_e32 v36, v36, v153
	v_min_f32_e32 v5, v27, v155
	v_max_f32_e32 v27, v27, v155
	v_min_f32_e32 v24, v38, v23
	v_max_f32_e32 v38, v38, v23
	v_min_f32_e32 v10, v29, v14
	v_max_f32_e32 v29, v29, v14
	v_min_f32_e32 v9, v32, v21
	v_max_f32_e32 v32, v32, v21
	v_min_f32_e32 v149, v154, v40
	v_max_f32_e32 v154, v154, v40
	v_min_f32_e32 v140, v34, v38
	v_max_f32_e32 v34, v34, v38
	v_min_f32_e32 v148, v145, v29
	v_max_f32_e32 v145, v145, v29
	v_min_f32_e32 v143, v36, v32
	v_max_f32_e32 v36, v36, v32
	v_min_f32_e32 v142, v27, v154
	v_max_f32_e32 v27, v27, v154
	v_min_f32_e32 v8, v139, v24
	v_max_f32_e32 v139, v139, v24
	v_min_f32_e32 v6, v7, v10
	v_max_f32_e32 v7, v7, v10
	v_min_f32_e32 v135, v144, v9
	v_max_f32_e32 v144, v144, v9
	v_min_f32_e32 v141, v5, v149
	v_max_f32_e32 v5, v5, v149
	v_min_f32_e32 v150, v34, v36
	v_max_f32_e32 v34, v34, v36
	v_min_f32_e32 v19, v145, v27
	v_max_f32_e32 v145, v145, v27
	v_min_f32_e32 v49, v140, v143
	v_max_f32_e32 v140, v140, v143
	v_min_f32_e32 v33, v148, v142
	v_max_f32_e32 v148, v148, v142
	v_min_f32_e32 v64, v139, v144
	v_max_f32_e32 v139, v139, v144
	v_min_f32_e32 v4, v7, v5
	v_max_f32_e32 v7, v7, v5
; DI void phase_peer_q(const Params& p, int layer, u16* lds, const int WAVE_S) {
;     ...
; #pragma unroll
;       for (int i = 0; i < 16; ++i) t[i] = -3.0e38f;
; #pragma unroll
;       for (int nt = 0; nt < 4; ++nt)
; #pragma unroll
;         for (int i = 0; i < 16; ++i) {
;           const uint32_t n = nt * 32 + (i & 3) + 8 * (i >> 2) + 4 * h;
;           const float v = __uint_as_float((__float_as_uint(acc[nt][0][i]) & ~127u) | n);
;           ins16n(t, v, nt * 16 + i);
;         }
;       float o16[16];
; #pragma unroll
;       for (int i = 0; i < 16; ++i) {
;         auto rr = __builtin_amdgcn_permlane32_swap(__float_as_uint(t[i]), __float_as_uint(t[i]), false, false);
;         o16[i] = __uint_as_float(h ? rr[0] : rr[1]);
;       }
	v_min_f32_e32 v137, v8, v135
	v_max_f32_e32 v8, v8, v135
	v_min_f32_e32 v62, v6, v141
	v_max_f32_e32 v6, v6, v141
	v_min_f32_e32 v35, v34, v145
	v_max_f32_e32 v34, v34, v145
	v_min_f32_e32 v47, v150, v19
	v_max_f32_e32 v150, v150, v19
	v_min_f32_e32 v59, v140, v148
	v_max_f32_e32 v140, v140, v148
	v_min_f32_e32 v12, v49, v33
	v_max_f32_e32 v49, v49, v33
	v_min_f32_e32 v51, v139, v7
	v_max_f32_e32 v139, v139, v7
	v_min_f32_e32 v134, v64, v4
	v_max_f32_e32 v64, v64, v4
	v_min_f32_e32 v63, v8, v6
	v_max_f32_e32 v8, v8, v6
	v_min_f32_e32 v46, v137, v62
	v_max_f32_e32 v137, v137, v62
	v_max_f32_e32 v2, v2, v46
	v_max_f32_e32 v11, v11, v137
	v_max_f32_e32 v28, v28, v63
	v_max_f32_e32 v22, v22, v8
	v_max_f32_e32 v53, v53, v134
	v_max_f32_e32 v13, v13, v64
	v_max_f32_e32 v44, v44, v51
	v_max_f32_e32 v16, v16, v139
	v_max_f32_e32 v3, v3, v12
	v_max_f32_e32 v152, v152, v49
	v_max_f32_e32 v60, v60, v59
	v_max_f32_e32 v26, v26, v140
	v_max_f32_e32 v55, v55, v47
	v_max_f32_e32 v25, v25, v150
	v_max_f32_e32 v138, v138, v35
	v_max_f32_e32 v136, v136, v34
	v_min_f32_e32 v65, v2, v3
	v_max_f32_e32 v2, v2, v3
	v_min_f32_e32 v61, v11, v152
	v_max_f32_e32 v11, v11, v152
	v_min_f32_e32 v18, v28, v60
	v_max_f32_e32 v28, v28, v60
	v_min_f32_e32 v31, v22, v26
	v_max_f32_e32 v22, v22, v26
	v_min_f32_e32 v20, v53, v55
	v_max_f32_e32 v53, v53, v55
	v_min_f32_e32 v50, v13, v25
	v_max_f32_e32 v13, v13, v25
	v_min_f32_e32 v151, v44, v138
	v_max_f32_e32 v44, v44, v138
	v_min_f32_e32 v52, v16, v136
	v_max_f32_e32 v16, v16, v136
	v_min_f32_e32 v43, v2, v53
	v_max_f32_e32 v2, v2, v53
	v_min_f32_e32 v54, v11, v13
	v_max_f32_e32 v11, v11, v13
	v_min_f32_e32 v45, v28, v44
	v_max_f32_e32 v28, v28, v44
	v_min_f32_e32 v48, v22, v16
	v_max_f32_e32 v22, v22, v16
	v_min_f32_e32 v0, v65, v20
	v_max_f32_e32 v65, v65, v20
	v_min_f32_e32 v58, v61, v50
	v_max_f32_e32 v61, v61, v50
	v_min_f32_e32 v57, v18, v151
	v_max_f32_e32 v18, v18, v151
	v_min_f32_e32 v15, v31, v52
	v_max_f32_e32 v31, v31, v52
	v_min_f32_e32 v17, v2, v28
	v_max_f32_e32 v2, v2, v28
	v_min_f32_e32 v39, v11, v22
	v_max_f32_e32 v11, v11, v22
	v_min_f32_e32 v30, v43, v45
	v_max_f32_e32 v43, v43, v45
	v_min_f32_e32 v37, v54, v48
	v_max_f32_e32 v54, v54, v48
	v_min_f32_e32 v56, v65, v18
	v_max_f32_e32 v65, v65, v18
	v_min_f32_e32 v42, v61, v31
	v_max_f32_e32 v61, v61, v31
	v_min_f32_e32 v41, v0, v57
	v_max_f32_e32 v0, v0, v57
	v_min_f32_e32 v153, v58, v15
	v_max_f32_e32 v58, v58, v15
	v_min_f32_e32 v155, v2, v11
	v_max_f32_e32 v2, v2, v11
	v_min_f32_e32 v23, v17, v39
	v_max_f32_e32 v17, v17, v39
	v_min_f32_e32 v14, v43, v54
	v_max_f32_e32 v43, v43, v54
	v_min_f32_e32 v21, v30, v37
	v_max_f32_e32 v30, v30, v37
	v_min_f32_e32 v40, v65, v61
	v_max_f32_e32 v65, v65, v61
	v_min_f32_e32 v38, v56, v42
	v_max_f32_e32 v56, v56, v42
	v_min_f32_e32 v29, v0, v58
	v_max_f32_e32 v0, v0, v58
	v_min_f32_e32 v32, v41, v153
	v_max_f32_e32 v41, v41, v153
	v_mov_b32_e32 v16, v17
	v_mov_b32_e32 v15, v23
	v_mov_b32_e32 v13, v14
	v_mov_b32_e32 v12, v30
	v_mov_b32_e32 v11, v21
	v_mov_b32_e32 v10, v65
	v_mov_b32_e32 v9, v40
	v_mov_b32_e32 v8, v56
	v_mov_b32_e32 v7, v38
	v_mov_b32_e32 v6, v0
	v_mov_b32_e32 v5, v29
	v_mov_b32_e32 v4, v41
	v_mov_b32_e32 v3, v32
	v_mov_b32_e32 v0, v2
	v_mov_b32_e32 v17, v155
	v_mov_b32_e32 v14, v43
	v_mov_b32_e32 v2, v0
	v_mov_b32_e32 v18, v0
	s_nop 1
	v_permlane32_swap_b32_e32 v2, v18
	v_cndmask_b32_e64 v2, v2, v18, s[34:35]
	v_mov_b32_e32 v18, v17
	v_mov_b32_e32 v19, v17
	s_nop 1
	v_permlane32_swap_b32_e32 v18, v19
	v_cndmask_b32_e64 v18, v18, v19, s[34:35]
	v_mov_b32_e32 v19, v16
	v_mov_b32_e32 v20, v16
	s_nop 1
	v_permlane32_swap_b32_e32 v19, v20
	v_cndmask_b32_e64 v19, v19, v20, s[34:35]
	v_mov_b32_e32 v20, v15
	v_mov_b32_e32 v21, v15
	s_nop 1
	v_permlane32_swap_b32_e32 v20, v21
	v_cndmask_b32_e64 v20, v20, v21, s[34:35]
	v_mov_b32_e32 v21, v14
	v_mov_b32_e32 v22, v14
	s_nop 1
	v_permlane32_swap_b32_e32 v21, v22
	v_cndmask_b32_e64 v21, v21, v22, s[34:35]
	v_mov_b32_e32 v22, v13
	v_mov_b32_e32 v23, v13
	s_nop 1
; DI void phase_peer_q(const Params& p, int layer, u16* lds, const int WAVE_S) {
;     ...
;       float o16[16];
; #pragma unroll
;       for (int i = 0; i < 16; ++i) {
;         auto rr = __builtin_amdgcn_permlane32_swap(__float_as_uint(t[i]), __float_as_uint(t[i]), false, false);
;         o16[i] = __uint_as_float(h ? rr[0] : rr[1]);
;       }
; #pragma unroll
;       for (int i = 0; i < 16; ++i) ins16(t, o16[i]);
	v_permlane32_swap_b32_e32 v22, v23
	v_cndmask_b32_e64 v22, v22, v23, s[34:35]
	v_mov_b32_e32 v23, v12
	v_mov_b32_e32 v24, v12
	s_nop 1
	v_permlane32_swap_b32_e32 v23, v24
	v_cndmask_b32_e64 v23, v23, v24, s[34:35]
	v_mov_b32_e32 v24, v11
	v_mov_b32_e32 v25, v11
	s_nop 1
	v_permlane32_swap_b32_e32 v24, v25
	v_cndmask_b32_e64 v24, v24, v25, s[34:35]
	v_mov_b32_e32 v25, v10
	v_mov_b32_e32 v26, v10
	s_nop 1
	v_permlane32_swap_b32_e32 v25, v26
	v_cndmask_b32_e64 v25, v25, v26, s[34:35]
	v_mov_b32_e32 v26, v9
	v_mov_b32_e32 v27, v9
	s_nop 1
	v_permlane32_swap_b32_e32 v26, v27
	v_cndmask_b32_e64 v26, v26, v27, s[34:35]
	v_mov_b32_e32 v27, v8
	v_mov_b32_e32 v28, v8
	s_nop 1
	v_permlane32_swap_b32_e32 v27, v28
	v_cndmask_b32_e64 v27, v27, v28, s[34:35]
	v_mov_b32_e32 v28, v7
	v_mov_b32_e32 v29, v7
	s_nop 1
	v_permlane32_swap_b32_e32 v28, v29
	v_cndmask_b32_e64 v28, v28, v29, s[34:35]
	v_mov_b32_e32 v29, v6
	v_mov_b32_e32 v30, v6
	s_nop 1
	v_permlane32_swap_b32_e32 v29, v30
	v_cndmask_b32_e64 v29, v29, v30, s[34:35]
	v_mov_b32_e32 v30, v5
	v_mov_b32_e32 v31, v5
	s_nop 1
	v_permlane32_swap_b32_e32 v30, v31
	v_cndmask_b32_e64 v30, v30, v31, s[34:35]
	v_mov_b32_e32 v31, v4
	v_mov_b32_e32 v32, v4
	s_nop 1
	v_permlane32_swap_b32_e32 v31, v32
	v_cndmask_b32_e64 v31, v31, v32, s[34:35]
	v_mov_b32_e32 v32, v3
	v_mov_b32_e32 v33, v3
	s_nop 1
	v_permlane32_swap_b32_e32 v32, v33
	v_cndmask_b32_e64 v32, v32, v33, s[34:35]
	v_max_f32_e32 v0, v0, v32
	v_max_f32_e32 v17, v17, v31
	v_max_f32_e32 v16, v16, v30
	v_max_f32_e32 v15, v15, v29
	v_max_f32_e32 v14, v14, v28
	v_max_f32_e32 v13, v13, v27
	v_max_f32_e32 v12, v12, v26
	v_max_f32_e32 v11, v11, v25
	v_max_f32_e32 v10, v10, v24
	v_max_f32_e32 v9, v9, v23
	v_max_f32_e32 v8, v8, v22
	v_max_f32_e32 v7, v7, v21
	v_max_f32_e32 v6, v6, v20
	v_max_f32_e32 v5, v5, v19
	v_max_f32_e32 v4, v4, v18
	v_max_f32_e32 v3, v3, v2
	v_min_f32_e32 v25, v0, v10
	v_max_f32_e32 v2, v0, v10
	v_min_f32_e32 v26, v17, v9
	v_max_f32_e32 v18, v17, v9
	v_min_f32_e32 v27, v16, v8
	v_max_f32_e32 v19, v16, v8
	v_min_f32_e32 v28, v15, v7
	v_max_f32_e32 v20, v15, v7
	v_min_f32_e32 v29, v14, v6
	v_max_f32_e32 v21, v14, v6
	v_min_f32_e32 v30, v13, v5
	v_max_f32_e32 v22, v13, v5
	v_min_f32_e32 v31, v12, v4
	v_max_f32_e32 v23, v12, v4
	v_min_f32_e32 v32, v11, v3
	v_max_f32_e32 v24, v11, v3
	v_min_f32_e32 v14, v2, v21
	v_max_f32_e32 v0, v2, v21
	v_min_f32_e32 v13, v18, v22
	v_max_f32_e32 v17, v18, v22
	v_min_f32_e32 v12, v19, v23
	v_max_f32_e32 v16, v19, v23
	v_min_f32_e32 v11, v20, v24
	v_max_f32_e32 v15, v20, v24
	v_min_f32_e32 v6, v25, v29
	v_max_f32_e32 v10, v25, v29
	v_min_f32_e32 v5, v26, v30
	v_max_f32_e32 v9, v26, v30
	v_min_f32_e32 v4, v27, v31
	v_max_f32_e32 v8, v27, v31
	v_min_f32_e32 v3, v28, v32
	v_max_f32_e32 v7, v28, v32
	v_min_f32_e32 v19, v0, v16
	v_max_f32_e32 v2, v0, v16
	v_min_f32_e32 v20, v17, v15
	v_max_f32_e32 v18, v17, v15
	v_min_f32_e32 v23, v14, v12
	v_max_f32_e32 v21, v14, v12
	v_min_f32_e32 v24, v13, v11
	v_max_f32_e32 v22, v13, v11
	v_min_f32_e32 v27, v10, v8
	v_max_f32_e32 v25, v10, v8
	v_min_f32_e32 v28, v9, v7
	v_max_f32_e32 v26, v9, v7
	v_min_f32_e32 v31, v6, v4
	v_max_f32_e32 v29, v6, v4
	v_min_f32_e32 v32, v5, v3
	v_max_f32_e32 v30, v5, v3
	v_min_f32_e32 v3, v2, v18
	v_max_f32_e32 v2, v2, v18
	v_min_f32_e32 v5, v19, v20
	v_max_f32_e32 v4, v19, v20
	v_min_f32_e32 v7, v21, v22
	v_max_f32_e32 v6, v21, v22
	v_min_f32_e32 v9, v23, v24
	v_max_f32_e32 v8, v23, v24
	v_min_f32_e32 v17, v25, v26
	v_max_f32_e32 v16, v25, v26
	v_min_f32_e32 v15, v27, v28
	v_max_f32_e32 v14, v27, v28
	v_min_f32_e32 v13, v29, v30
	v_max_f32_e32 v12, v29, v30
	v_min_f32_e32 v11, v31, v32
	v_max_f32_e32 v10, v31, v32
	s_cbranch_vccz .LBB0_388
	v_mov_b64_e32 v[18:19], v[98:99]
	v_mov_b64_e32 v[20:21], v[100:101]
	v_mov_b64_e32 v[22:23], v[102:103]
	v_mov_b64_e32 v[24:25], v[104:105]
	v_mov_b64_e32 v[26:27], v[106:107]
	v_mov_b64_e32 v[28:29], v[108:109]
	v_mov_b64_e32 v[30:31], v[110:111]
	v_mov_b64_e32 v[32:33], v[112:113]
	s_branch .LBB0_389
